# MLA: softmax scale folded into the latent q (f32, before bf16 rounding) and -m0 into the QK accumulator init; v_exp reads the MFMA result directly (32 fewer VALU per key tile)
# speedup vs baseline: 1.0511x; 1.0072x over previous
; template <int NCH, bool ROPE>
; DI void norm_rows16(int lane, size_t row0, bool is_ctx, int t0, const bf16_t* srcA, size_t ldA, int nA, const bf16_t* srcB, size_t ldB,
;                     const float* st, int st_idx, const float* gain, float inv_n, bf16_t* dst, size_t ldd, const float* tab) {
;     ...
;   const bool actv = sub < NCH, fromA = sub < nA;
;   float gv[8];
; #pragma unroll
;   for (int j = 0; j < 8; ++j) gv[j] = actv ? gain[sub * 8 + j] : 0.f;
;   u32x4 ua[16];
;   float prea[16];
; #pragma unroll
;   for (int it = 0; it < 16; ++it) {
;     const size_t row = row0 + it * 4 + tq;
;     ua[it] = (u32x4){0u, 0u, 0u, 0u};
;     if (actv) ua[it] = *(const u32x4*)(fromA ? srcA + row * ldA + sub * 8 : srcB + row * ldB + (sub - nA) * 8);
; DI void finalize_wave_item(const Params& p, int l, int wi) {
;     ...
;   if (part == 0) {
;     norm_rows16<12, true>(lane, row0, is_ctx, t0, qk0 + h * 96, QKW, 12, qk0, QKW, st0, 0, p.g_mla_q + l * 96, 1.f / 96.f,
;                           (bf16_t*)(ws + O_MQ) + h * 96, 768, tab);
.LBB0_788:
	s_or_b64 exec, exec, s[0:1]
	s_waitcnt vmcnt(0)
	v_mov_b32_e32 v160, 0x3e16c740
	v_cndmask_b32_e64 v160, v160, 1.0, s[42:43]
	v_mul_f32_e32 v72, v160, v72
	v_mul_f32_e32 v73, v160, v73
	v_mul_f32_e32 v74, v160, v74
	v_mul_f32_e32 v75, v160, v75
	v_mul_f32_e32 v76, v160, v76
	v_mul_f32_e32 v77, v160, v77
	v_mul_f32_e32 v78, v160, v78
	v_mul_f32_e32 v79, v160, v79
	v_mul_u32_u24_e32 v0, 0x60, v126
	v_readlane_b32 s0, v251, 47
	v_lshlrev_b32_e32 v0, 1, v0
	v_readlane_b32 s1, v251, 48
	v_lshrrev_b32_e32 v81, 4, v125
	v_lshlrev_b32_e32 v108, 1, v70
	v_lshl_add_u64 v[2:3], s[0:1], 0, v[0:1]
	v_mov_b32_e32 v109, v1
	v_or_b32_e32 v106, v68, v81
	v_mov_b32_e32 v107, v69
	v_lshl_add_u64 v[70:71], v[2:3], 0, v[108:109]
	v_mov_b32_e32 v63, 0
	v_mov_b32_e32 v64, 0
	v_mov_b32_e32 v65, 0
	s_and_saveexec_b64 s[0:1], vcc
	s_cbranch_execz .LBB0_790
	s_movk_i32 s26, 0xe00
	v_mad_u64_u32 v[2:3], s[18:19], v106, s26, v[70:71]
	v_mov_b32_e32 v4, v3
	v_mad_u64_u32 v[4:5], s[18:19], v107, s26, v[4:5]
	v_mov_b32_e32 v3, v4
	global_load_dwordx4 v[62:65], v[2:3], off

; template <int DQK, bool NA, bool SMAX, int LDV> ...
;     ...
;     const char* ks = smem + cur * STG;
;     const char* vs = ks + KBYTES;
;     f32x4 s[4][2];
; #pragma unroll
;     for (int kt = 0; kt < 4; ++kt) { s[kt][0] = (f32x4){0.f, 0.f, 0.f, 0.f}; s[kt][1] = (f32x4){0.f, 0.f, 0.f, 0.f}; }
; #pragma unroll
;     for (int ds = 0; ds < NDS; ++ds) {
;       bf16x8 kf[4];
; #pragma unroll
;       for (int kt = 0; kt < 4; ++kt) kf[kt] = *(const bf16x8*)(ks + (kt * 16 + fr) * KSTR + ds * 64 + fq * 16);
; #pragma unroll
;       for (int kt = 0; kt < 4; ++kt) {
;         s[kt][0] = __builtin_amdgcn_mfma_f32_16x16x32_bf16(kf[kt], qf[0][ds], s[kt][0], 0, 0, 0);
;         s[kt][1] = __builtin_amdgcn_mfma_f32_16x16x32_bf16(kf[kt], qf[1][ds], s[kt][1], 0, 0, 0);
;       }
;     }
;     bf16x8 vfr[2][4];
; #pragma unroll
;     for (int k2 = 0; k2 < 2; ++k2)
; #pragma unroll
;       for (int d = 0; d < 4; ++d) {
;         const char* vp = vs + (k2 * 32 + fq * 4 + (fr >> 2)) * VSTR + d * 32 + (fr & 3) * 8;
;         typedef short s16x4_t __attribute__((ext_vector_type(4)));
;         const s16x4_t lo = __builtin_amdgcn_ds_read_tr16_b64_v4i16((__attribute__((address_space(3))) s16x4_t*)(vp));
;         const s16x4_t hi = __builtin_amdgcn_ds_read_tr16_b64_v4i16((__attribute__((address_space(3))) s16x4_t*)(vp + 16 * VSTR));
;         vfr[k2][d] = __builtin_shufflevector(lo, hi, 0, 1, 2, 3, 4, 5, 6, 7);
;       }
;     ...
; #pragma unroll
;         for (int kt = 0; kt < 4; ++kt)
; #pragma unroll
;           for (int j = 0; j < 4; ++j) { const float tv = s[kt][qt][j] * c1; s[kt][qt][j] = tv; mx = fmaxf(mx, tv); }
;       }
;       mx = fmaxf(mx, __shfl_xor(mx, 16));
.LBB0_1114:
	ds_read_b128 v[84:87], v207
	ds_read_b128 v[88:91], v207 offset:3584
	ds_read_b128 v[92:95], v207 offset:7168
	ds_read_b128 v[96:99], v207 offset:10752
	ds_read_b128 v[116:119], v207 offset:64
	ds_read_b128 v[120:123], v207 offset:3648
	ds_read_b128 v[124:127], v207 offset:7232
	ds_read_b128 v[128:131], v207 offset:10816
	s_waitcnt lgkmcnt(7)
	v_mfma_f32_16x16x32_bf16 v[100:103], v[84:87], v[16:19], 0
	v_mfma_f32_16x16x32_bf16 v[84:87], v[84:87], v[28:31], 0
	s_waitcnt lgkmcnt(6)
	v_mfma_f32_16x16x32_bf16 v[104:107], v[88:91], v[16:19], 0
	v_mfma_f32_16x16x32_bf16 v[88:91], v[88:91], v[28:31], 0
	s_waitcnt lgkmcnt(5)
	v_mfma_f32_16x16x32_bf16 v[108:111], v[92:95], v[16:19], 0
	v_mfma_f32_16x16x32_bf16 v[92:95], v[92:95], v[28:31], 0
	s_waitcnt lgkmcnt(4)
	v_mfma_f32_16x16x32_bf16 v[112:115], v[96:99], v[16:19], 0
	v_mfma_f32_16x16x32_bf16 v[96:99], v[96:99], v[28:31], 0
	s_waitcnt lgkmcnt(3)
	v_mfma_f32_16x16x32_bf16 v[100:103], v[116:119], v[20:23], v[100:103]
	v_mfma_f32_16x16x32_bf16 v[84:87], v[116:119], v[32:35], v[84:87]
	s_waitcnt lgkmcnt(2)
	v_mfma_f32_16x16x32_bf16 v[104:107], v[120:123], v[20:23], v[104:107]
	v_mfma_f32_16x16x32_bf16 v[88:91], v[120:123], v[32:35], v[88:91]
	ds_read_b128 v[116:119], v207 offset:128
	ds_read_b128 v[120:123], v207 offset:3712
	ds_read_b128 v[144:147], v207 offset:7296
	ds_read_b128 v[154:157], v207 offset:10880
	s_waitcnt lgkmcnt(5)
	v_mfma_f32_16x16x32_bf16 v[108:111], v[124:127], v[20:23], v[108:111]
	v_mfma_f32_16x16x32_bf16 v[92:95], v[124:127], v[32:35], v[92:95]
	s_waitcnt lgkmcnt(4)
	v_mfma_f32_16x16x32_bf16 v[112:115], v[128:131], v[20:23], v[112:115]
	v_mfma_f32_16x16x32_bf16 v[96:99], v[128:131], v[32:35], v[96:99]
	s_waitcnt lgkmcnt(3)
	v_mfma_f32_16x16x32_bf16 v[158:161], v[116:119], v[24:27], v[100:103]
	v_mfma_f32_16x16x32_bf16 v[128:131], v[116:119], v[36:39], v[84:87]
	s_waitcnt lgkmcnt(2)
	v_mfma_f32_16x16x32_bf16 v[162:165], v[120:123], v[24:27], v[104:107]
	v_mfma_f32_16x16x32_bf16 v[124:127], v[120:123], v[36:39], v[88:91]
	s_waitcnt lgkmcnt(1)
	v_mfma_f32_16x16x32_bf16 v[174:177], v[144:147], v[24:27], v[108:111]
	v_mfma_f32_16x16x32_bf16 v[120:123], v[144:147], v[36:39], v[92:95]
	s_waitcnt lgkmcnt(0)
	v_mfma_f32_16x16x32_bf16 v[178:181], v[154:157], v[24:27], v[112:115]
	v_mfma_f32_16x16x32_bf16 v[116:119], v[154:157], v[36:39], v[96:99]
	s_nop 1
	ds_read_b64_tr_b16 v[114:115], v208 offset:16896
	ds_read_b64_tr_b16 v[112:113], v208 offset:14336
	ds_read_b64_tr_b16 v[108:109], v208 offset:14368
	ds_read_b64_tr_b16 v[110:111], v208 offset:16928
	ds_read_b64_tr_b16 v[104:105], v208 offset:14400
	ds_read_b64_tr_b16 v[106:107], v208 offset:16960
	ds_read_b64_tr_b16 v[96:97], v208 offset:14432
	ds_read_b64_tr_b16 v[98:99], v208 offset:16992
	ds_read_b64_tr_b16 v[84:85], v208 offset:19456
	ds_read_b64_tr_b16 v[86:87], v208 offset:22016
	ds_read_b64_tr_b16 v[88:89], v208 offset:19488
	ds_read_b64_tr_b16 v[90:91], v208 offset:22048
	ds_read_b64_tr_b16 v[92:93], v208 offset:19520
	ds_read_b64_tr_b16 v[94:95], v208 offset:22080
	ds_read_b64_tr_b16 v[100:101], v208 offset:19552
	ds_read_b64_tr_b16 v[102:103], v208 offset:22112
	v_mul_f32_e32 v0, 1.0, v158
	v_mul_f32_e32 v2, 1.0, v159
	v_max3_f32 v0, v0, s3, v2
	v_mul_f32_e32 v2, 1.0, v160
	v_mul_f32_e32 v3, 1.0, v161
	v_max3_f32 v0, v0, v2, v3
	v_mul_f32_e32 v2, 1.0, v162
	v_mul_f32_e32 v3, 1.0, v163
	v_max3_f32 v0, v0, v2, v3
	v_mul_f32_e32 v2, 1.0, v164
	v_mul_f32_e32 v3, 1.0, v165
	v_max3_f32 v0, v0, v2, v3
	v_mul_f32_e32 v2, 1.0, v174
	v_mul_f32_e32 v3, 1.0, v175
	v_max3_f32 v0, v0, v2, v3
	v_mul_f32_e32 v2, 1.0, v176
	v_mul_f32_e32 v3, 1.0, v177
	v_max3_f32 v0, v0, v2, v3
	v_mul_f32_e32 v2, 1.0, v178
	v_mul_f32_e32 v3, 1.0, v179
	v_max3_f32 v0, v0, v2, v3
	v_mul_f32_e32 v2, 1.0, v180
	v_mul_f32_e32 v3, 1.0, v181
	v_max3_f32 v0, v0, v2, v3
	ds_bpermute_b32 v2, v198, v0
	v_mul_f32_e32 v3, 1.0, v129
	v_mul_f32_e32 v144, 1.0, v131
	s_waitcnt lgkmcnt(0)
	v_max_f32_e32 v2, v2, v2
	v_max_f32_e32 v0, v0, v2
	ds_bpermute_b32 v2, v197, v0
	s_waitcnt lgkmcnt(0)
; DI unsigned cvt_pk_bf16(float lo, float hi) { f32x2_t v = {lo, hi}; bf16x2_t b = __builtin_convertvector(v, bf16x2_t); return __builtin_bit_cast(unsigned, b); }
; template <int DQK, bool NA, bool SMAX, int LDV> ...
;     ...
;       mx = fmaxf(mx, __shfl_xor(mx, 16));
;       mx = fmaxf(mx, __shfl_xor(mx, 32));
;       const float mnew = fmaxf(mrun[qt], mx);
;       const float alpha = __builtin_amdgcn_exp2f(mrun[qt] - mnew);
;       mrun[qt] = mnew;
;       float sum = 0.f;
; #pragma unroll
;       for (int kt = 0; kt < 4; ++kt)
; #pragma unroll
;         for (int j = 0; j < 4; ++j) { const float pv = __builtin_amdgcn_exp2f(s[kt][qt][j] - mnew); s[kt][qt][j] = pv; sum += pv; }
;       lrun[qt] = lrun[qt] * alpha + sum;
; #pragma unroll
;       for (int d = 0; d < 4; ++d) o[d][qt] = o[d][qt] * alpha;
;     }
;     }
; #pragma unroll
;     for (int k2 = 0; k2 < 2; ++k2) {
;       bf16x8 pf[2];
; #pragma unroll
;       for (int qt = 0; qt < 2; ++qt) {
;         u32x4 u;
;         u[0] = cvt_pk_bf16(s[2 * k2][qt][0], s[2 * k2][qt][1]); u[1] = cvt_pk_bf16(s[2 * k2][qt][2], s[2 * k2][qt][3]);
;         u[2] = cvt_pk_bf16(s[2 * k2 + 1][qt][0], s[2 * k2 + 1][qt][1]); u[3] = cvt_pk_bf16(s[2 * k2 + 1][qt][2], s[2 * k2 + 1][qt][3]);
;         pf[qt] = __builtin_bit_cast(bf16x8, u);
;       }
; #pragma unroll
;       for (int d = 0; d < 4; ++d) {
;         o[d][0] = __builtin_amdgcn_mfma_f32_16x16x32_bf16(vfr[k2][d], pf[0], o[d][0], 0, 0, 0);
;         o[d][1] = __builtin_amdgcn_mfma_f32_16x16x32_bf16(vfr[k2][d], pf[1], o[d][1], 0, 0, 0);
;       }
;     }
	v_max3_f32 v150, v226, v0, v2
	v_fma_f32 v2, v158, 1.0, -v150
	v_exp_f32_e32 v209, v2
	v_fma_f32 v2, v159, 1.0, -v150
	v_exp_f32_e32 v210, v2
	v_fma_f32 v2, v160, 1.0, -v150
	v_exp_f32_e32 v211, v2
	v_fma_f32 v2, v161, 1.0, -v150
	v_exp_f32_e32 v212, v2
	v_fma_f32 v2, v162, 1.0, -v150
	v_exp_f32_e32 v213, v2
	v_fma_f32 v2, v163, 1.0, -v150
	v_exp_f32_e32 v214, v2
	v_fma_f32 v2, v164, 1.0, -v150
	v_exp_f32_e32 v215, v2
	v_fma_f32 v2, v165, 1.0, -v150
	v_exp_f32_e32 v216, v2
	v_fma_f32 v2, v174, 1.0, -v150
	v_exp_f32_e32 v145, v2
	v_fma_f32 v2, v175, 1.0, -v150
	v_exp_f32_e32 v147, v2
	v_fma_f32 v2, v176, 1.0, -v150
	v_exp_f32_e32 v155, v2
	v_fma_f32 v2, v177, 1.0, -v150
	v_exp_f32_e32 v157, v2
	v_fma_f32 v2, v178, 1.0, -v150
	v_exp_f32_e32 v159, v2
	v_fma_f32 v2, v179, 1.0, -v150
	v_exp_f32_e32 v161, v2
	v_fma_f32 v2, v180, 1.0, -v150
	v_exp_f32_e32 v163, v2
	v_fma_f32 v2, v181, 1.0, -v150
	v_exp_f32_e32 v165, v2
	v_mul_f32_e32 v2, 1.0, v128
	v_max3_f32 v2, v2, s3, v3
	v_mul_f32_e32 v3, 1.0, v130
	v_max3_f32 v2, v2, v3, v144
	v_mul_f32_e32 v3, 1.0, v124
	v_mul_f32_e32 v144, 1.0, v125
	v_max3_f32 v2, v2, v3, v144
	v_mul_f32_e32 v3, 1.0, v126
	v_mul_f32_e32 v144, 1.0, v127
	v_max3_f32 v2, v2, v3, v144
	v_mul_f32_e32 v3, 1.0, v120
	v_mul_f32_e32 v144, 1.0, v121
	v_max3_f32 v2, v2, v3, v144
	v_mul_f32_e32 v3, 1.0, v122
	v_mul_f32_e32 v144, 1.0, v123
	v_max3_f32 v2, v2, v3, v144
	v_mul_f32_e32 v3, 1.0, v116
	v_mul_f32_e32 v144, 1.0, v117
	v_max3_f32 v2, v2, v3, v144
	v_mul_f32_e32 v3, 1.0, v118
	v_mul_f32_e32 v144, 1.0, v119
	v_max3_f32 v2, v2, v3, v144
	ds_bpermute_b32 v3, v198, v2
	v_sub_f32_e32 v0, v226, v150
	v_exp_f32_e32 v0, v0
	s_waitcnt lgkmcnt(0)
	v_max_f32_e32 v3, v3, v3
	v_max_f32_e32 v2, v2, v3
	ds_bpermute_b32 v3, v197, v2
	v_pk_mul_f32 v[82:83], v[82:83], v[0:1] op_sel_hi:[1,0]
	v_pk_mul_f32 v[80:81], v[80:81], v[0:1] op_sel_hi:[1,0]
	v_pk_mul_f32 v[78:79], v[78:79], v[0:1] op_sel_hi:[1,0]
	v_pk_mul_f32 v[76:77], v[76:77], v[0:1] op_sel_hi:[1,0]
	s_waitcnt lgkmcnt(0)
	v_max3_f32 v167, v225, v2, v3
	v_fma_f32 v3, v128, 1.0, -v167
	v_exp_f32_e32 v217, v3
	v_fma_f32 v3, v129, 1.0, -v167
	v_exp_f32_e32 v218, v3
	v_fma_f32 v3, v130, 1.0, -v167
	v_exp_f32_e32 v219, v3
	v_fma_f32 v3, v131, 1.0, -v167
	v_exp_f32_e32 v220, v3
	v_fma_f32 v3, v124, 1.0, -v167
	v_exp_f32_e32 v221, v3
	v_fma_f32 v3, v125, 1.0, -v167
	v_exp_f32_e32 v222, v3
	v_fma_f32 v3, v126, 1.0, -v167
	v_exp_f32_e32 v223, v3
	v_fma_f32 v3, v127, 1.0, -v167
	v_exp_f32_e32 v224, v3
	v_fma_f32 v3, v120, 1.0, -v167
	v_exp_f32_e32 v144, v3
	v_fma_f32 v3, v121, 1.0, -v167
	v_exp_f32_e32 v146, v3
	v_fma_f32 v3, v122, 1.0, -v167
	v_sub_f32_e32 v2, v225, v167
	v_exp_f32_e32 v154, v3
	v_fma_f32 v3, v123, 1.0, -v167
	v_exp_f32_e32 v156, v3
	v_fma_f32 v3, v116, 1.0, -v167
	v_exp_f32_e32 v166, v2
	v_exp_f32_e32 v158, v3
	v_fma_f32 v3, v117, 1.0, -v167
	v_exp_f32_e32 v160, v3
	v_fma_f32 v3, v118, 1.0, -v167
	v_exp_f32_e32 v162, v3
	v_fma_f32 v3, v119, 1.0, -v167
	v_exp_f32_e32 v164, v3
	v_pk_mul_f32 v[74:75], v[74:75], v[0:1] op_sel_hi:[1,0]
	v_pk_mul_f32 v[72:73], v[72:73], v[0:1] op_sel_hi:[1,0]
	v_pk_mul_f32 v[70:71], v[70:71], v[0:1] op_sel_hi:[1,0]
	v_pk_mul_f32 v[68:69], v[68:69], v[0:1] op_sel_hi:[1,0]
	v_pk_mul_f32 v[66:67], v[66:67], v[166:167] op_sel_hi:[1,0]
	v_pk_mul_f32 v[64:65], v[64:65], v[166:167] op_sel_hi:[1,0]
	v_pk_mul_f32 v[14:15], v[14:15], v[166:167] op_sel_hi:[1,0]
	v_pk_mul_f32 v[12:13], v[12:13], v[166:167] op_sel_hi:[1,0]
	v_pk_mul_f32 v[10:11], v[10:11], v[166:167] op_sel_hi:[1,0]
	v_pk_mul_f32 v[8:9], v[8:9], v[166:167] op_sel_hi:[1,0]
	v_pk_mul_f32 v[6:7], v[6:7], v[166:167] op_sel_hi:[1,0]
	v_pk_mul_f32 v[4:5], v[4:5], v[166:167] op_sel_hi:[1,0]
	v_cvt_pk_bf16_f32 v116, v209, v210
	v_cvt_pk_bf16_f32 v117, v211, v212
	v_cvt_pk_bf16_f32 v118, v213, v214
	v_cvt_pk_bf16_f32 v119, v215, v216
	v_cvt_pk_bf16_f32 v120, v217, v218
	v_cvt_pk_bf16_f32 v121, v219, v220
	v_cvt_pk_bf16_f32 v122, v221, v222
	v_cvt_pk_bf16_f32 v123, v223, v224
	v_mfma_f32_16x16x32_bf16 v[80:83], v[112:115], v[116:119], v[80:83]
	s_nop 0
	v_mfma_f32_16x16x32_bf16 v[64:67], v[112:115], v[120:123], v[64:67]
	v_mfma_f32_16x16x32_bf16 v[76:79], v[108:111], v[116:119], v[76:79]
	v_mfma_f32_16x16x32_bf16 v[12:15], v[108:111], v[120:123], v[12:15]
	v_mfma_f32_16x16x32_bf16 v[108:111], v[104:107], v[116:119], v[72:75]
	v_mfma_f32_16x16x32_bf16 v[104:107], v[104:107], v[120:123], v[8:11]
	v_mfma_f32_16x16x32_bf16 v[112:115], v[96:99], v[116:119], v[68:71]
	v_cvt_pk_bf16_f32 v116, v145, v147
	v_cvt_pk_bf16_f32 v117, v155, v157
	v_cvt_pk_bf16_f32 v118, v159, v161
	v_mfma_f32_16x16x32_bf16 v[96:99], v[96:99], v[120:123], v[4:7]
	v_cvt_pk_bf16_f32 v119, v163, v165
	v_cvt_pk_bf16_f32 v120, v144, v146
	v_cvt_pk_bf16_f32 v121, v154, v156
	v_cvt_pk_bf16_f32 v122, v158, v160
	v_cvt_pk_bf16_f32 v123, v162, v164
	v_mfma_f32_16x16x32_bf16 v[68:71], v[84:87], v[116:119], v[80:83]
	s_nop 0
	v_mfma_f32_16x16x32_bf16 v[2:5], v[84:87], v[120:123], v[64:67]
	v_mfma_f32_16x16x32_bf16 v[72:75], v[88:91], v[116:119], v[76:79]
	v_mfma_f32_16x16x32_bf16 v[6:9], v[88:91], v[120:123], v[12:15]
	v_mfma_f32_16x16x32_bf16 v[76:79], v[92:95], v[116:119], v[108:111]
	v_mfma_f32_16x16x32_bf16 v[10:13], v[92:95], v[120:123], v[104:107]
	v_mfma_f32_16x16x32_bf16 v[80:83], v[100:103], v[116:119], v[112:115]
	v_mfma_f32_16x16x32_bf16 v[64:67], v[100:103], v[120:123], v[96:99]
	s_and_saveexec_b64 s[50:51], s[40:41]
	s_cbranch_execz .LBB0_1116
	v_add_u32_e32 v14, v205, v152
	s_waitcnt vmcnt(2)
	ds_write_b128 v14, v[48:51] offset:24576

; template <int DQK, bool NA, bool SMAX, int LDV> ...
;     ...
;     const char* ks = smem + cur * STG;
;     const char* vs = ks + KBYTES;
;     f32x4 s[4][2];
; #pragma unroll
;     for (int kt = 0; kt < 4; ++kt) { s[kt][0] = (f32x4){0.f, 0.f, 0.f, 0.f}; s[kt][1] = (f32x4){0.f, 0.f, 0.f, 0.f}; }
; #pragma unroll
;     for (int ds = 0; ds < NDS; ++ds) {
;       bf16x8 kf[4];
; #pragma unroll
;       for (int kt = 0; kt < 4; ++kt) kf[kt] = *(const bf16x8*)(ks + (kt * 16 + fr) * KSTR + ds * 64 + fq * 16);
; #pragma unroll
;       for (int kt = 0; kt < 4; ++kt) {
;         s[kt][0] = __builtin_amdgcn_mfma_f32_16x16x32_bf16(kf[kt], qf[0][ds], s[kt][0], 0, 0, 0);
;         s[kt][1] = __builtin_amdgcn_mfma_f32_16x16x32_bf16(kf[kt], qf[1][ds], s[kt][1], 0, 0, 0);
;       }
;     }
;     bf16x8 vfr[2][4];
; #pragma unroll
;     for (int k2 = 0; k2 < 2; ++k2)
; #pragma unroll
;       for (int d = 0; d < 4; ++d) {
;         const char* vp = vs + (k2 * 32 + fq * 4 + (fr >> 2)) * VSTR + d * 32 + (fr & 3) * 8;
;         typedef short s16x4_t __attribute__((ext_vector_type(4)));
;         const s16x4_t lo = __builtin_amdgcn_ds_read_tr16_b64_v4i16((__attribute__((address_space(3))) s16x4_t*)(vp));
;         const s16x4_t hi = __builtin_amdgcn_ds_read_tr16_b64_v4i16((__attribute__((address_space(3))) s16x4_t*)(vp + 16 * VSTR));
;         vfr[k2][d] = __builtin_shufflevector(lo, hi, 0, 1, 2, 3, 4, 5, 6, 7);
;       }
;     ...
; #pragma unroll
;         for (int kt = 0; kt < 4; ++kt)
; #pragma unroll
;           for (int j = 0; j < 4; ++j) { const float tv = s[kt][qt][j] * c1; s[kt][qt][j] = tv; mx = fmaxf(mx, tv); }
;       }
;       mx = fmaxf(mx, __shfl_xor(mx, 16));
.LBB0_1120:
	ds_read_b128 v[84:87], v207 offset:24576
	ds_read_b128 v[88:91], v207 offset:28160
	ds_read_b128 v[92:95], v207 offset:31744
	ds_read_b128 v[96:99], v207 offset:35328
	ds_read_b128 v[116:119], v207 offset:24640
	ds_read_b128 v[120:123], v207 offset:28224
	ds_read_b128 v[124:127], v207 offset:31808
	ds_read_b128 v[128:131], v207 offset:35392
	s_waitcnt lgkmcnt(7)
	v_mfma_f32_16x16x32_bf16 v[100:103], v[84:87], v[16:19], 0
	v_mfma_f32_16x16x32_bf16 v[84:87], v[84:87], v[28:31], 0
	s_waitcnt lgkmcnt(6)
	v_mfma_f32_16x16x32_bf16 v[104:107], v[88:91], v[16:19], 0
	v_mfma_f32_16x16x32_bf16 v[88:91], v[88:91], v[28:31], 0
	s_waitcnt lgkmcnt(5)
	v_mfma_f32_16x16x32_bf16 v[108:111], v[92:95], v[16:19], 0
	v_mfma_f32_16x16x32_bf16 v[92:95], v[92:95], v[28:31], 0
	s_waitcnt lgkmcnt(4)
	v_mfma_f32_16x16x32_bf16 v[112:115], v[96:99], v[16:19], 0
	v_mfma_f32_16x16x32_bf16 v[96:99], v[96:99], v[28:31], 0
	s_waitcnt lgkmcnt(3)
	v_mfma_f32_16x16x32_bf16 v[100:103], v[116:119], v[20:23], v[100:103]
	v_mfma_f32_16x16x32_bf16 v[84:87], v[116:119], v[32:35], v[84:87]
	s_waitcnt lgkmcnt(2)
	v_mfma_f32_16x16x32_bf16 v[104:107], v[120:123], v[20:23], v[104:107]
	v_mfma_f32_16x16x32_bf16 v[88:91], v[120:123], v[32:35], v[88:91]
	ds_read_b128 v[116:119], v207 offset:24704
	ds_read_b128 v[120:123], v207 offset:28288
	ds_read_b128 v[168:171], v207 offset:31872
	ds_read_b128 v[172:175], v207 offset:35456
	s_waitcnt lgkmcnt(5)
	v_mfma_f32_16x16x32_bf16 v[108:111], v[124:127], v[20:23], v[108:111]
	v_mfma_f32_16x16x32_bf16 v[92:95], v[124:127], v[32:35], v[92:95]
	s_waitcnt lgkmcnt(4)
	v_mfma_f32_16x16x32_bf16 v[112:115], v[128:131], v[20:23], v[112:115]
	v_mfma_f32_16x16x32_bf16 v[96:99], v[128:131], v[32:35], v[96:99]
	s_waitcnt lgkmcnt(3)
	v_mfma_f32_16x16x32_bf16 v[176:179], v[116:119], v[24:27], v[100:103]
	v_mfma_f32_16x16x32_bf16 v[128:131], v[116:119], v[36:39], v[84:87]
	s_waitcnt lgkmcnt(2)
	v_mfma_f32_16x16x32_bf16 v[180:183], v[120:123], v[24:27], v[104:107]
	v_mfma_f32_16x16x32_bf16 v[124:127], v[120:123], v[36:39], v[88:91]
	s_waitcnt lgkmcnt(1)
	v_mfma_f32_16x16x32_bf16 v[184:187], v[168:171], v[24:27], v[108:111]
	v_mfma_f32_16x16x32_bf16 v[120:123], v[168:171], v[36:39], v[92:95]
	s_waitcnt lgkmcnt(0)
	v_mfma_f32_16x16x32_bf16 v[240:243], v[172:175], v[24:27], v[112:115]
	v_mfma_f32_16x16x32_bf16 v[116:119], v[172:175], v[36:39], v[96:99]
	s_nop 1
	ds_read_b64_tr_b16 v[114:115], v208 offset:41472
	ds_read_b64_tr_b16 v[112:113], v208 offset:38912
	ds_read_b64_tr_b16 v[108:109], v208 offset:38944
	ds_read_b64_tr_b16 v[110:111], v208 offset:41504
	ds_read_b64_tr_b16 v[104:105], v208 offset:38976
	ds_read_b64_tr_b16 v[106:107], v208 offset:41536
	ds_read_b64_tr_b16 v[96:97], v208 offset:39008
	ds_read_b64_tr_b16 v[98:99], v208 offset:41568
	ds_read_b64_tr_b16 v[84:85], v208 offset:44032
	ds_read_b64_tr_b16 v[86:87], v208 offset:46592
	ds_read_b64_tr_b16 v[88:89], v208 offset:44064
	ds_read_b64_tr_b16 v[90:91], v208 offset:46624
	ds_read_b64_tr_b16 v[92:93], v208 offset:44096
	ds_read_b64_tr_b16 v[94:95], v208 offset:46656
	ds_read_b64_tr_b16 v[100:101], v208 offset:44128
	ds_read_b64_tr_b16 v[102:103], v208 offset:46688
	v_mul_f32_e32 v14, 1.0, v176
	v_mul_f32_e32 v15, 1.0, v177
	v_max3_f32 v14, v14, s3, v15
	v_mul_f32_e32 v15, 1.0, v178
	v_mul_f32_e32 v168, 1.0, v179
	v_max3_f32 v14, v14, v15, v168
	v_mul_f32_e32 v15, 1.0, v180
	v_mul_f32_e32 v168, 1.0, v181
	v_max3_f32 v14, v14, v15, v168
	v_mul_f32_e32 v15, 1.0, v182
	v_mul_f32_e32 v168, 1.0, v183
	v_max3_f32 v14, v14, v15, v168
	v_mul_f32_e32 v15, 1.0, v184
	v_mul_f32_e32 v168, 1.0, v185
	v_max3_f32 v14, v14, v15, v168
	v_mul_f32_e32 v15, 1.0, v186
	v_mul_f32_e32 v168, 1.0, v187
	v_max3_f32 v14, v14, v15, v168
	v_mul_f32_e32 v15, 1.0, v240
	v_mul_f32_e32 v168, 1.0, v241
	v_max3_f32 v14, v14, v15, v168
	v_mul_f32_e32 v15, 1.0, v242
	v_mul_f32_e32 v168, 1.0, v243
	v_max3_f32 v14, v14, v15, v168
	ds_bpermute_b32 v15, v198, v14
	v_mul_f32_e32 v168, 1.0, v131
	s_andn2_b64 vcc, exec, s[46:47]
	s_waitcnt lgkmcnt(0)
	v_max_f32_e32 v15, v15, v15
	v_max_f32_e32 v14, v14, v15
	ds_bpermute_b32 v15, v197, v14
	s_waitcnt lgkmcnt(0)
; DI unsigned cvt_pk_bf16(float lo, float hi) { f32x2_t v = {lo, hi}; bf16x2_t b = __builtin_convertvector(v, bf16x2_t); return __builtin_bit_cast(unsigned, b); }
; template <int DQK, bool NA, bool SMAX, int LDV> ...
;     ...
;       mx = fmaxf(mx, __shfl_xor(mx, 16));
;       mx = fmaxf(mx, __shfl_xor(mx, 32));
;       const float mnew = fmaxf(mrun[qt], mx);
;       const float alpha = __builtin_amdgcn_exp2f(mrun[qt] - mnew);
;       mrun[qt] = mnew;
;       float sum = 0.f;
; #pragma unroll
;       for (int kt = 0; kt < 4; ++kt)
; #pragma unroll
;         for (int j = 0; j < 4; ++j) { const float pv = __builtin_amdgcn_exp2f(s[kt][qt][j] - mnew); s[kt][qt][j] = pv; sum += pv; }
;       lrun[qt] = lrun[qt] * alpha + sum;
; #pragma unroll
;       for (int d = 0; d < 4; ++d) o[d][qt] = o[d][qt] * alpha;
;     }
;     }
; #pragma unroll
;     for (int k2 = 0; k2 < 2; ++k2) {
;       bf16x8 pf[2];
; #pragma unroll
;       for (int qt = 0; qt < 2; ++qt) {
;         u32x4 u;
;         u[0] = cvt_pk_bf16(s[2 * k2][qt][0], s[2 * k2][qt][1]); u[1] = cvt_pk_bf16(s[2 * k2][qt][2], s[2 * k2][qt][3]);
;         u[2] = cvt_pk_bf16(s[2 * k2 + 1][qt][0], s[2 * k2 + 1][qt][1]); u[3] = cvt_pk_bf16(s[2 * k2 + 1][qt][2], s[2 * k2 + 1][qt][3]);
;         pf[qt] = __builtin_bit_cast(bf16x8, u);
;       }
; #pragma unroll
;       for (int d = 0; d < 4; ++d) {
;         o[d][0] = __builtin_amdgcn_mfma_f32_16x16x32_bf16(vfr[k2][d], pf[0], o[d][0], 0, 0, 0);
;         o[d][1] = __builtin_amdgcn_mfma_f32_16x16x32_bf16(vfr[k2][d], pf[1], o[d][1], 0, 0, 0);
;       }
;     }
;     if (more) {
;       char* nx = smem + (cur ^ 1) * STG;
; #pragma unroll
;       for (int i = 0; i < NKC; ++i) if (kval[i]) *(u32x4*)(nx + kkey[i] * KSTR + kcc[i] * 16) = rk_wr[i];
;       *(u32x4*)(nx + KBYTES + vdv * VSTR + vcc * 16) = rv_wr;
;     }
	v_max3_f32 v226, v150, v14, v15
	v_fma_f32 v15, v176, 1.0, -v226
	v_exp_f32_e32 v227, v15
	v_fma_f32 v15, v177, 1.0, -v226
	v_exp_f32_e32 v228, v15
	v_fma_f32 v15, v178, 1.0, -v226
	v_exp_f32_e32 v229, v15
	v_fma_f32 v15, v179, 1.0, -v226
	v_exp_f32_e32 v230, v15
	v_fma_f32 v15, v180, 1.0, -v226
	v_exp_f32_e32 v231, v15
	v_fma_f32 v15, v181, 1.0, -v226
	v_exp_f32_e32 v232, v15
	v_fma_f32 v15, v182, 1.0, -v226
	v_exp_f32_e32 v169, v15
	v_fma_f32 v15, v183, 1.0, -v226
	v_exp_f32_e32 v171, v15
	v_fma_f32 v15, v184, 1.0, -v226
	v_exp_f32_e32 v173, v15
	v_fma_f32 v15, v185, 1.0, -v226
	v_exp_f32_e32 v175, v15
	v_fma_f32 v15, v186, 1.0, -v226
	v_exp_f32_e32 v177, v15
	v_fma_f32 v15, v187, 1.0, -v226
	v_exp_f32_e32 v179, v15
	v_fma_f32 v15, v240, 1.0, -v226
	v_exp_f32_e32 v181, v15
	v_fma_f32 v15, v241, 1.0, -v226
	v_exp_f32_e32 v183, v15
	v_fma_f32 v15, v242, 1.0, -v226
	v_sub_f32_e32 v14, v150, v226
	v_exp_f32_e32 v185, v15
	v_fma_f32 v15, v243, 1.0, -v226
	v_exp_f32_e32 v187, v15
	v_exp_f32_e32 v150, v14
	v_mul_f32_e32 v14, 1.0, v128
	v_mul_f32_e32 v15, 1.0, v129
	v_max3_f32 v14, v14, s3, v15
	v_mul_f32_e32 v15, 1.0, v130
	v_max3_f32 v14, v14, v15, v168
	v_mul_f32_e32 v15, 1.0, v124
	v_mul_f32_e32 v168, 1.0, v125
	v_max3_f32 v14, v14, v15, v168
	v_mul_f32_e32 v15, 1.0, v126
	v_mul_f32_e32 v168, 1.0, v127
	v_max3_f32 v14, v14, v15, v168
	v_mul_f32_e32 v15, 1.0, v120
	v_mul_f32_e32 v168, 1.0, v121
	v_max3_f32 v14, v14, v15, v168
	v_mul_f32_e32 v15, 1.0, v122
	v_mul_f32_e32 v168, 1.0, v123
	v_max3_f32 v14, v14, v15, v168
	v_mul_f32_e32 v15, 1.0, v116
	v_mul_f32_e32 v168, 1.0, v117
	v_max3_f32 v14, v14, v15, v168
	v_mul_f32_e32 v15, 1.0, v118
	v_mul_f32_e32 v168, 1.0, v119
	v_max3_f32 v14, v14, v15, v168
	ds_bpermute_b32 v15, v198, v14
	v_pk_mul_f32 v[70:71], v[70:71], v[150:151] op_sel_hi:[1,0]
	v_pk_mul_f32 v[68:69], v[68:69], v[150:151] op_sel_hi:[1,0]
	v_pk_mul_f32 v[74:75], v[74:75], v[150:151] op_sel_hi:[1,0]
	v_pk_mul_f32 v[72:73], v[72:73], v[150:151] op_sel_hi:[1,0]
	s_waitcnt lgkmcnt(0)
	v_max_f32_e32 v15, v15, v15
	v_max_f32_e32 v14, v14, v15
	ds_bpermute_b32 v15, v197, v14
	v_pk_mul_f32 v[78:79], v[78:79], v[150:151] op_sel_hi:[1,0]
	v_pk_mul_f32 v[76:77], v[76:77], v[150:151] op_sel_hi:[1,0]
	v_pk_mul_f32 v[82:83], v[82:83], v[150:151] op_sel_hi:[1,0]
	v_pk_mul_f32 v[80:81], v[80:81], v[150:151] op_sel_hi:[1,0]
	s_waitcnt lgkmcnt(0)
	v_max3_f32 v225, v167, v14, v15
	v_fma_f32 v15, v128, 1.0, -v225
	v_exp_f32_e32 v128, v15
	v_fma_f32 v15, v129, 1.0, -v225
	v_exp_f32_e32 v129, v15
	v_fma_f32 v15, v130, 1.0, -v225
	v_exp_f32_e32 v130, v15
	v_fma_f32 v15, v131, 1.0, -v225
	v_exp_f32_e32 v131, v15
	v_fma_f32 v15, v124, 1.0, -v225
	v_exp_f32_e32 v124, v15
	v_fma_f32 v15, v125, 1.0, -v225
	v_exp_f32_e32 v125, v15
	v_fma_f32 v15, v126, 1.0, -v225
	v_exp_f32_e32 v168, v15
	v_fma_f32 v15, v127, 1.0, -v225
	v_exp_f32_e32 v170, v15
	v_fma_f32 v15, v120, 1.0, -v225
	v_exp_f32_e32 v172, v15
	v_fma_f32 v15, v121, 1.0, -v225
	v_exp_f32_e32 v174, v15
	v_fma_f32 v15, v122, 1.0, -v225
	v_sub_f32_e32 v14, v167, v225
	v_exp_f32_e32 v176, v15
	v_fma_f32 v15, v123, 1.0, -v225
	v_exp_f32_e32 v178, v15
	v_fma_f32 v15, v116, 1.0, -v225
	v_exp_f32_e32 v116, v14
	v_exp_f32_e32 v180, v15
	v_fma_f32 v15, v117, 1.0, -v225
	v_exp_f32_e32 v182, v15
	v_fma_f32 v15, v118, 1.0, -v225
	v_exp_f32_e32 v184, v15
	v_fma_f32 v15, v119, 1.0, -v225
	v_exp_f32_e32 v186, v15
	v_pk_mul_f32 v[4:5], v[4:5], v[116:117] op_sel_hi:[1,0]
	v_pk_mul_f32 v[2:3], v[2:3], v[116:117] op_sel_hi:[1,0]
	v_pk_mul_f32 v[8:9], v[8:9], v[116:117] op_sel_hi:[1,0]
	v_pk_mul_f32 v[6:7], v[6:7], v[116:117] op_sel_hi:[1,0]
	v_pk_mul_f32 v[12:13], v[12:13], v[116:117] op_sel_hi:[1,0]
	v_pk_mul_f32 v[10:11], v[10:11], v[116:117] op_sel_hi:[1,0]
	v_pk_mul_f32 v[66:67], v[66:67], v[116:117] op_sel_hi:[1,0]
	v_pk_mul_f32 v[64:65], v[64:65], v[116:117] op_sel_hi:[1,0]
	v_cvt_pk_bf16_f32 v118, v227, v228
	v_cvt_pk_bf16_f32 v119, v229, v230
	v_cvt_pk_bf16_f32 v120, v231, v232
	v_cvt_pk_bf16_f32 v121, v169, v171
	v_cvt_pk_bf16_f32 v240, v128, v129
	v_cvt_pk_bf16_f32 v241, v130, v131
	v_cvt_pk_bf16_f32 v242, v124, v125
	v_cvt_pk_bf16_f32 v243, v168, v170
	v_mfma_f32_16x16x32_bf16 v[68:71], v[112:115], v[118:121], v[68:71]
	s_nop 0
	v_mfma_f32_16x16x32_bf16 v[2:5], v[112:115], v[240:243], v[2:5]
	v_mfma_f32_16x16x32_bf16 v[72:75], v[108:111], v[118:121], v[72:75]
	v_mfma_f32_16x16x32_bf16 v[6:9], v[108:111], v[240:243], v[6:9]
	v_mfma_f32_16x16x32_bf16 v[108:111], v[104:107], v[118:121], v[76:79]
	v_mfma_f32_16x16x32_bf16 v[104:107], v[104:107], v[240:243], v[10:13]
	v_mfma_f32_16x16x32_bf16 v[112:115], v[96:99], v[118:121], v[80:83]
	v_cvt_pk_bf16_f32 v118, v173, v175
	v_cvt_pk_bf16_f32 v119, v177, v179
	v_cvt_pk_bf16_f32 v120, v181, v183
	v_mfma_f32_16x16x32_bf16 v[96:99], v[96:99], v[240:243], v[64:67]
	v_cvt_pk_bf16_f32 v121, v185, v187
	v_cvt_pk_bf16_f32 v240, v172, v174
	v_cvt_pk_bf16_f32 v241, v176, v178
	v_cvt_pk_bf16_f32 v242, v180, v182
	v_cvt_pk_bf16_f32 v243, v184, v186
	v_mfma_f32_16x16x32_bf16 v[80:83], v[84:87], v[118:121], v[68:71]
	s_nop 0
	v_mfma_f32_16x16x32_bf16 v[64:67], v[84:87], v[240:243], v[2:5]
	v_mfma_f32_16x16x32_bf16 v[76:79], v[88:91], v[118:121], v[72:75]
	v_mfma_f32_16x16x32_bf16 v[12:15], v[88:91], v[240:243], v[6:9]
	v_mfma_f32_16x16x32_bf16 v[72:75], v[92:95], v[118:121], v[108:111]
	v_mfma_f32_16x16x32_bf16 v[8:11], v[92:95], v[240:243], v[104:107]
	v_mfma_f32_16x16x32_bf16 v[68:71], v[100:103], v[118:121], v[112:115]
	v_mfma_f32_16x16x32_bf16 v[4:7], v[100:103], v[240:243], v[96:99]
	s_cbranch_vccnz .LBB0_1111
	s_and_saveexec_b64 s[46:47], s[40:41]
	v_add_u32_e32 v2, v205, v152
	ds_write_b128 v2, v[40:43]
	s_or_b64 exec, exec, s[46:47]
	s_and_saveexec_b64 s[46:47], s[48:49]
	s_cbranch_execz .LBB0_1110
	v_add_u32_e32 v2, v206, v189
	ds_write_b128 v2, v[44:47]
	s_branch .LBB0_1110

; template <int DQK, bool NA, bool SMAX, int LDV> ...
;     ...
;   u32x4 rkA[NKC], rvA, rkB[NKC], rvB;
;   int kkey[NKC], kcc[NKC];
;   bool kval[NKC];
; #pragma unroll
;   for (int i = 0; i < NKC; ++i) { const int c = tid + i * 512; kval[i] = c < 64 * CPK; kkey[i] = kval[i] ? c / CPK : 0; kcc[i] = kval[i] ? c - kkey[i] * CPK : 0; }
;   const int vdv = tid >> 3, vcc = tid & 7;
;   {
; #pragma unroll
;     for (int i = 0; i < NKC; ++i) rkA[i] = *(const u32x4*)(Kp + (size_t)kkey[i] * ldk + kcc[i] * 8);
;     rvA = *(const u32x4*)(Vp + (size_t)vdv * LDV + vcc * 8);
;     if (nkt > 1) {
;       const int kb = 64;
; #pragma unroll
;       for (int i = 0; i < NKC; ++i) rkB[i] = *(const u32x4*)(Kp + (size_t)(kb + kkey[i]) * ldk + kcc[i] * 8);
;       rvB = *(const u32x4*)(Vp + (size_t)(kb + vdv) * LDV + vcc * 8);
;     }
; #pragma unroll
;     for (int i = 0; i < NKC; ++i) if (kval[i]) *(u32x4*)(smem + kkey[i] * KSTR + kcc[i] * 16) = rkA[i];
;     *(u32x4*)(smem + KBYTES + vdv * VSTR + vcc * 16) = rvA;
;   }
;   __syncthreads();
;   f32x4 o[4][2];
;   float mrun[2], lrun[2];
; #pragma unroll
;   for (int qt = 0; qt < 2; ++qt) {
;     mrun[qt] = -1e30f; lrun[qt] = 0.f;
; #pragma unroll
;     for (int d = 0; d < 4; ++d) o[d][qt] = (f32x4){0.f, 0.f, 0.f, 0.f};
;   }
.LBB0_1133:
	s_or_b64 exec, exec, s[4:5]
	s_movk_i32 s26, 0x600
	v_mad_i64_i32 v[64:65], s[4:5], v14, s26, 0
	v_mad_i64_i32 v[14:15], s[4:5], v15, s26, 0
	s_movk_i32 s4, 0xa0
	s_nop 0
	v_mul_lo_u32 v6, v6, s4
	v_add_u32_e32 v6, 0, v6
	v_add_u32_e32 v173, v6, v0
	v_lshlrev_b32_e32 v172, 2, v13
	v_lshrrev_b32_e32 v6, 2, v12
	s_add_u32 s4, s53, s52
	v_or_b32_e32 v6, v172, v6
	s_addc_u32 s5, 0, 0
	v_lshl_add_u32 v11, v13, 4, 0
	v_mul_u32_u24_e32 v13, 0xa0, v6
	v_add_u32_e32 v174, 0, v7
	v_lshl_add_u64 v[6:7], s[4:5], 0, v[8:9]
	s_add_u32 s4, s33, s19
	s_addc_u32 s5, 0, 0
	v_mul_u32_u24_e32 v66, 0xe0, v12
	v_lshlrev_b32_e32 v12, 3, v12
	v_lshl_add_u64 v[120:121], v[6:7], 0, v[0:1]
	v_lshl_add_u64 v[6:7], s[4:5], 0, v[14:15]
	v_and_b32_e32 v12, 24, v12
	v_lshl_add_u64 v[124:125], v[4:5], 1, v[6:7]
	v_lshl_add_u64 v[4:5], s[4:5], 0, v[64:65]
	v_add_u32_e32 v12, 0, v12
	v_lshl_add_u64 v[126:127], v[2:3], 1, v[4:5]
	v_mov_b32_e32 v4, 0
	v_ashrrev_i32_e32 v119, 31, v118
	v_ashrrev_i32_e32 v117, 31, v116
	v_add_u32_e32 v175, 0, v10
	s_mov_b32 s19, 0
	v_add_u32_e32 v0, v11, v66
	v_add_u32_e32 v176, v12, v13
	v_mov_b32_e32 v5, v4
	v_mov_b32_e32 v6, v4
	v_mov_b32_e32 v7, v4
	v_mov_b32_e32 v64, v4
	v_mov_b32_e32 v65, v4
	v_mov_b32_e32 v66, v4
	v_mov_b32_e32 v67, v4
	v_mov_b32_e32 v8, v4
	v_mov_b32_e32 v9, v4
	v_mov_b32_e32 v10, v4
	v_mov_b32_e32 v11, v4
	v_mov_b32_e32 v68, v4
	v_mov_b32_e32 v69, v4
	v_mov_b32_e32 v70, v4
	v_mov_b32_e32 v71, v4
	v_mov_b32_e32 v12, v4
	v_mov_b32_e32 v13, v4
	v_mov_b32_e32 v14, v4
	v_mov_b32_e32 v15, v4
	v_mov_b32_e32 v76, v4
	v_mov_b32_e32 v77, v4
	v_mov_b32_e32 v78, v4
	v_mov_b32_e32 v79, v4
	v_mov_b32_e32 v72, v4
	v_mov_b32_e32 v73, v4
	v_mov_b32_e32 v74, v4
	v_mov_b32_e32 v75, v4
	v_mov_b32_e32 v80, v4
	v_mov_b32_e32 v81, v4
	v_mov_b32_e32 v82, v4
	v_mov_b32_e32 v83, v4
	v_mov_b32_e32 v122, v4
	v_mov_b32_e32 v123, v4
	s_waitcnt vmcnt(3)
	ds_write_b128 v173, v[52:55] offset:14336
	s_waitcnt lgkmcnt(0)
	s_barrier
	v_sub_f32_e32 v244, 0, v188
	v_sub_f32_e32 v245, 0, v188
	v_sub_f32_e32 v246, 0, v188
	v_sub_f32_e32 v247, 0, v188
	s_branch .LBB0_1136

; template <int DQK, bool NA, bool SMAX, int LDV> ...
;     ...
;     f32x4 s[4][2];
; #pragma unroll
;     for (int kt = 0; kt < 4; ++kt) { s[kt][0] = (f32x4){0.f, 0.f, 0.f, 0.f}; s[kt][1] = (f32x4){0.f, 0.f, 0.f, 0.f}; }
; #pragma unroll
;     for (int ds = 0; ds < NDS; ++ds) {
;       bf16x8 kf[4];
; #pragma unroll
;       for (int kt = 0; kt < 4; ++kt) kf[kt] = *(const bf16x8*)(ks + (kt * 16 + fr) * KSTR + ds * 64 + fq * 16);
; #pragma unroll
;       for (int kt = 0; kt < 4; ++kt) {
;         s[kt][0] = __builtin_amdgcn_mfma_f32_16x16x32_bf16(kf[kt], qf[0][ds], s[kt][0], 0, 0, 0);
;         s[kt][1] = __builtin_amdgcn_mfma_f32_16x16x32_bf16(kf[kt], qf[1][ds], s[kt][1], 0, 0, 0);
;       }
;     }
;     bf16x8 vfr[2][4];
; #pragma unroll
;     for (int k2 = 0; k2 < 2; ++k2)
; #pragma unroll
;       for (int d = 0; d < 4; ++d) {
;         const char* vp = vs + (k2 * 32 + fq * 4 + (fr >> 2)) * VSTR + d * 32 + (fr & 3) * 8;
;         typedef short s16x4_t __attribute__((ext_vector_type(4)));
;         const s16x4_t lo = __builtin_amdgcn_ds_read_tr16_b64_v4i16((__attribute__((address_space(3))) s16x4_t*)(vp));
;         const s16x4_t hi = __builtin_amdgcn_ds_read_tr16_b64_v4i16((__attribute__((address_space(3))) s16x4_t*)(vp + 16 * VSTR));
;         vfr[k2][d] = __builtin_shufflevector(lo, hi, 0, 1, 2, 3, 4, 5, 6, 7);
;       }
;     __builtin_amdgcn_sched_barrier(0);
;     if (SMAX) {
; #pragma unroll
;       for (int qt = 0; qt < 2; ++qt) {
;         float sum = 0.f;
;         if (NA && it >= 4) {
;           const int kr = rs + (it - 4);
;           const int ql = w * 32 + qt * 16 + fr, qr = r0 + (ql >> 6), qc = ql & 63;
;           const int rst = min(max(qr - 4, 0), 24);
;           const bool rowok = (kr >= rst) && (kr < rst + 8);
;           const int cst = min(max(qc - 8, 0), 48);
;           const int base = (kr - qr + 7) * 31 + 15 - qc;
;           float bv[4][4];
; #pragma unroll
;           for (int kt = 0; kt < 4; ++kt)
; #pragma unroll
;             for (int j = 0; j < 4; ++j) bv[kt][j] = rpbl[min(max(base + kt * 16 + fq * 4 + j, 0), 464)];
; #pragma unroll
;           for (int kt = 0; kt < 4; ++kt)
; #pragma unroll
;             for (int j = 0; j < 4; ++j) {
;               const int kc = kt * 16 + fq * 4 + j;
;               const float okf = (rowok && (kc >= cst) && (kc < cst + 16)) ? 1.f : 0.f;
.LBB0_1138:
	ds_read_b128 v[84:87], v0
	ds_read_b128 v[88:91], v0 offset:3584
	ds_read_b128 v[92:95], v0 offset:7168
	ds_read_b128 v[96:99], v0 offset:10752
	ds_read_b128 v[128:131], v0 offset:64
	ds_read_b128 v[132:135], v0 offset:3648
	ds_read_b128 v[136:139], v0 offset:7232
	ds_read_b128 v[140:143], v0 offset:10816
	s_waitcnt lgkmcnt(7)
	v_mfma_f32_16x16x32_bf16 v[100:103], v[84:87], v[16:19], v[244:247]
	v_mfma_f32_16x16x32_bf16 v[84:87], v[84:87], v[28:31], v[244:247]
	s_waitcnt lgkmcnt(6)
	v_mfma_f32_16x16x32_bf16 v[104:107], v[88:91], v[16:19], v[244:247]
	v_mfma_f32_16x16x32_bf16 v[88:91], v[88:91], v[28:31], v[244:247]
	s_waitcnt lgkmcnt(5)
	v_mfma_f32_16x16x32_bf16 v[108:111], v[92:95], v[16:19], v[244:247]
	v_mfma_f32_16x16x32_bf16 v[92:95], v[92:95], v[28:31], v[244:247]
	s_waitcnt lgkmcnt(4)
	v_mfma_f32_16x16x32_bf16 v[112:115], v[96:99], v[16:19], v[244:247]
	v_mfma_f32_16x16x32_bf16 v[96:99], v[96:99], v[28:31], v[244:247]
	s_waitcnt lgkmcnt(3)
	v_mfma_f32_16x16x32_bf16 v[100:103], v[128:131], v[20:23], v[100:103]
	v_mfma_f32_16x16x32_bf16 v[84:87], v[128:131], v[32:35], v[84:87]
	s_waitcnt lgkmcnt(2)
	v_mfma_f32_16x16x32_bf16 v[104:107], v[132:135], v[20:23], v[104:107]
	v_mfma_f32_16x16x32_bf16 v[88:91], v[132:135], v[32:35], v[88:91]
	s_waitcnt lgkmcnt(1)
	v_mfma_f32_16x16x32_bf16 v[108:111], v[136:139], v[20:23], v[108:111]
	v_mfma_f32_16x16x32_bf16 v[92:95], v[136:139], v[32:35], v[92:95]
	s_waitcnt lgkmcnt(0)
	v_mfma_f32_16x16x32_bf16 v[112:115], v[140:143], v[20:23], v[112:115]
	v_mfma_f32_16x16x32_bf16 v[96:99], v[140:143], v[32:35], v[96:99]
	ds_read_b128 v[128:131], v0 offset:128
	ds_read_b128 v[132:135], v0 offset:3712
	ds_read_b128 v[136:139], v0 offset:7296
	ds_read_b128 v[140:143], v0 offset:10880
	s_waitcnt lgkmcnt(3)
	v_mfma_f32_16x16x32_bf16 v[158:161], v[128:131], v[24:27], v[100:103]
	v_mfma_f32_16x16x32_bf16 v[162:165], v[128:131], v[36:39], v[84:87]
	s_waitcnt lgkmcnt(2)
	v_mfma_f32_16x16x32_bf16 v[128:131], v[132:135], v[24:27], v[104:107]
	v_mfma_f32_16x16x32_bf16 v[166:169], v[132:135], v[36:39], v[88:91]
	s_waitcnt lgkmcnt(1)
	v_mfma_f32_16x16x32_bf16 v[184:187], v[136:139], v[24:27], v[108:111]
	v_mfma_f32_16x16x32_bf16 v[206:209], v[136:139], v[36:39], v[92:95]
	s_waitcnt lgkmcnt(0)
	v_mfma_f32_16x16x32_bf16 v[210:213], v[140:143], v[24:27], v[112:115]
	v_mfma_f32_16x16x32_bf16 v[214:217], v[140:143], v[36:39], v[96:99]
	s_nop 1
	ds_read_b64_tr_b16 v[114:115], v176 offset:16896
	ds_read_b64_tr_b16 v[112:113], v176 offset:14336
	ds_read_b64_tr_b16 v[108:109], v176 offset:14368
	ds_read_b64_tr_b16 v[110:111], v176 offset:16928
	ds_read_b64_tr_b16 v[104:105], v176 offset:14400
	ds_read_b64_tr_b16 v[106:107], v176 offset:16960
	ds_read_b64_tr_b16 v[96:97], v176 offset:14432
	ds_read_b64_tr_b16 v[98:99], v176 offset:16992
	ds_read_b64_tr_b16 v[84:85], v176 offset:19456
	ds_read_b64_tr_b16 v[86:87], v176 offset:22016
	ds_read_b64_tr_b16 v[88:89], v176 offset:19488
	ds_read_b64_tr_b16 v[90:91], v176 offset:22048
	ds_read_b64_tr_b16 v[92:93], v176 offset:19520
	ds_read_b64_tr_b16 v[94:95], v176 offset:22080
	ds_read_b64_tr_b16 v[100:101], v176 offset:19552
	ds_read_b64_tr_b16 v[102:103], v176 offset:22112
	v_exp_f32_e32 v177, v158
	v_exp_f32_e32 v178, v159
	v_exp_f32_e32 v179, v160
	v_exp_f32_e32 v180, v161
	v_exp_f32_e32 v181, v128
	v_exp_f32_e32 v182, v129
	v_exp_f32_e32 v183, v130
	v_exp_f32_e32 v129, v131
	v_exp_f32_e32 v131, v184
	v_exp_f32_e32 v133, v185
	v_exp_f32_e32 v135, v186
	v_exp_f32_e32 v137, v187
	v_exp_f32_e32 v139, v210
	v_exp_f32_e32 v141, v211
	v_exp_f32_e32 v143, v212
	v_exp_f32_e32 v145, v213
	v_exp_f32_e32 v184, v162
	v_exp_f32_e32 v185, v163
	v_exp_f32_e32 v186, v164
	v_exp_f32_e32 v187, v165
	v_exp_f32_e32 v189, v166
	v_exp_f32_e32 v203, v167
	v_exp_f32_e32 v204, v168
	v_exp_f32_e32 v128, v169
	v_exp_f32_e32 v130, v206
	v_exp_f32_e32 v132, v207
	v_exp_f32_e32 v134, v208
	v_exp_f32_e32 v136, v209
	v_exp_f32_e32 v138, v214
	v_exp_f32_e32 v140, v215
	v_exp_f32_e32 v142, v216
	v_exp_f32_e32 v144, v217
	v_cvt_pk_bf16_f32 v158, v177, v178
	v_cvt_pk_bf16_f32 v159, v179, v180
	v_cvt_pk_bf16_f32 v160, v181, v182
	v_cvt_pk_bf16_f32 v161, v183, v129
	v_cvt_pk_bf16_f32 v162, v184, v185
	v_cvt_pk_bf16_f32 v163, v186, v187
	v_cvt_pk_bf16_f32 v164, v189, v203
	v_cvt_pk_bf16_f32 v165, v204, v128
	s_waitcnt lgkmcnt(14)
	v_mfma_f32_16x16x32_bf16 v[80:83], v[112:115], v[158:161], v[80:83]
	v_mfma_f32_16x16x32_bf16 v[72:75], v[112:115], v[162:165], v[72:75]
	s_waitcnt lgkmcnt(12)
	v_mfma_f32_16x16x32_bf16 v[112:115], v[108:111], v[158:161], v[76:79]
	v_mfma_f32_16x16x32_bf16 v[12:15], v[108:111], v[162:165], v[12:15]
	s_waitcnt lgkmcnt(10)
	v_mfma_f32_16x16x32_bf16 v[108:111], v[104:107], v[158:161], v[68:71]
	v_mfma_f32_16x16x32_bf16 v[8:11], v[104:107], v[162:165], v[8:11]
	s_waitcnt lgkmcnt(8)
	v_mfma_f32_16x16x32_bf16 v[104:107], v[96:99], v[158:161], v[64:67]
	v_cvt_pk_bf16_f32 v158, v130, v132
	v_cvt_pk_bf16_f32 v159, v134, v136
	v_cvt_pk_bf16_f32 v160, v138, v140
	v_mfma_f32_16x16x32_bf16 v[2:5], v[96:99], v[162:165], v[4:7]
	v_cvt_pk_bf16_f32 v96, v131, v133
	v_cvt_pk_bf16_f32 v97, v135, v137
	v_cvt_pk_bf16_f32 v98, v139, v141
	v_cvt_pk_bf16_f32 v99, v143, v145
	v_cvt_pk_bf16_f32 v161, v142, v144
	s_waitcnt lgkmcnt(6)
	v_mfma_f32_16x16x32_bf16 v[76:79], v[84:87], v[96:99], v[80:83]
	v_mfma_f32_16x16x32_bf16 v[80:83], v[84:87], v[158:161], v[72:75]
	s_waitcnt lgkmcnt(4)
	v_mfma_f32_16x16x32_bf16 v[72:75], v[88:91], v[96:99], v[112:115]
	v_mfma_f32_16x16x32_bf16 v[68:71], v[88:91], v[158:161], v[12:15]
	s_waitcnt lgkmcnt(2)
	v_mfma_f32_16x16x32_bf16 v[64:67], v[92:95], v[96:99], v[108:111]
	v_mfma_f32_16x16x32_bf16 v[10:13], v[92:95], v[158:161], v[8:11]
	s_waitcnt lgkmcnt(0)
	v_mfma_f32_16x16x32_bf16 v[6:9], v[100:103], v[96:99], v[104:107]
	v_mfma_f32_16x16x32_bf16 v[2:5], v[100:103], v[158:161], v[2:5]
	s_and_saveexec_b64 s[42:43], s[40:41]
	s_cbranch_execz .LBB0_1140
	v_add_u32_e32 v14, v174, v150
	s_waitcnt vmcnt(2)
	ds_write_b128 v14, v[48:51] offset:24576

; template <int DQK, bool NA, bool SMAX, int LDV> ...
;     ...
;     f32x4 s[4][2];
; #pragma unroll
;     for (int kt = 0; kt < 4; ++kt) { s[kt][0] = (f32x4){0.f, 0.f, 0.f, 0.f}; s[kt][1] = (f32x4){0.f, 0.f, 0.f, 0.f}; }
; #pragma unroll
;     for (int ds = 0; ds < NDS; ++ds) {
;       bf16x8 kf[4];
; #pragma unroll
;       for (int kt = 0; kt < 4; ++kt) kf[kt] = *(const bf16x8*)(ks + (kt * 16 + fr) * KSTR + ds * 64 + fq * 16);
; #pragma unroll
;       for (int kt = 0; kt < 4; ++kt) {
;         s[kt][0] = __builtin_amdgcn_mfma_f32_16x16x32_bf16(kf[kt], qf[0][ds], s[kt][0], 0, 0, 0);
;         s[kt][1] = __builtin_amdgcn_mfma_f32_16x16x32_bf16(kf[kt], qf[1][ds], s[kt][1], 0, 0, 0);
;       }
;     }
;     bf16x8 vfr[2][4];
; #pragma unroll
;     for (int k2 = 0; k2 < 2; ++k2)
; #pragma unroll
;       for (int d = 0; d < 4; ++d) {
;         const char* vp = vs + (k2 * 32 + fq * 4 + (fr >> 2)) * VSTR + d * 32 + (fr & 3) * 8;
;         typedef short s16x4_t __attribute__((ext_vector_type(4)));
;         const s16x4_t lo = __builtin_amdgcn_ds_read_tr16_b64_v4i16((__attribute__((address_space(3))) s16x4_t*)(vp));
;         const s16x4_t hi = __builtin_amdgcn_ds_read_tr16_b64_v4i16((__attribute__((address_space(3))) s16x4_t*)(vp + 16 * VSTR));
;         vfr[k2][d] = __builtin_shufflevector(lo, hi, 0, 1, 2, 3, 4, 5, 6, 7);
;       }
;     __builtin_amdgcn_sched_barrier(0);
;     if (SMAX) {
; #pragma unroll
;       for (int qt = 0; qt < 2; ++qt) {
;         float sum = 0.f;
;         if (NA && it >= 4) {
;           const int kr = rs + (it - 4);
;           const int ql = w * 32 + qt * 16 + fr, qr = r0 + (ql >> 6), qc = ql & 63;
;           const int rst = min(max(qr - 4, 0), 24);
;           const bool rowok = (kr >= rst) && (kr < rst + 8);
;           const int cst = min(max(qc - 8, 0), 48);
;           const int base = (kr - qr + 7) * 31 + 15 - qc;
;           float bv[4][4];
; #pragma unroll
;           for (int kt = 0; kt < 4; ++kt)
; #pragma unroll
;             for (int j = 0; j < 4; ++j) bv[kt][j] = rpbl[min(max(base + kt * 16 + fq * 4 + j, 0), 464)];
; #pragma unroll
;           for (int kt = 0; kt < 4; ++kt)
; #pragma unroll
;             for (int j = 0; j < 4; ++j) {
;               const int kc = kt * 16 + fq * 4 + j;
;               const float okf = (rowok && (kc >= cst) && (kc < cst + 16)) ? 1.f : 0.f;
.LBB0_1144:
	ds_read_b128 v[84:87], v0 offset:24576
	ds_read_b128 v[88:91], v0 offset:28160
	ds_read_b128 v[92:95], v0 offset:31744
	ds_read_b128 v[96:99], v0 offset:35328
	ds_read_b128 v[154:157], v0 offset:24640
	ds_read_b128 v[158:161], v0 offset:28224
	ds_read_b128 v[162:165], v0 offset:31808
	ds_read_b128 v[166:169], v0 offset:35392
	s_waitcnt lgkmcnt(7)
	v_mfma_f32_16x16x32_bf16 v[100:103], v[84:87], v[16:19], v[244:247]
	v_mfma_f32_16x16x32_bf16 v[84:87], v[84:87], v[28:31], v[244:247]
	s_waitcnt lgkmcnt(6)
	v_mfma_f32_16x16x32_bf16 v[104:107], v[88:91], v[16:19], v[244:247]
	v_mfma_f32_16x16x32_bf16 v[88:91], v[88:91], v[28:31], v[244:247]
	s_waitcnt lgkmcnt(5)
	v_mfma_f32_16x16x32_bf16 v[108:111], v[92:95], v[16:19], v[244:247]
	v_mfma_f32_16x16x32_bf16 v[92:95], v[92:95], v[28:31], v[244:247]
	s_waitcnt lgkmcnt(4)
	v_mfma_f32_16x16x32_bf16 v[112:115], v[96:99], v[16:19], v[244:247]
	v_mfma_f32_16x16x32_bf16 v[96:99], v[96:99], v[28:31], v[244:247]
	s_waitcnt lgkmcnt(3)
	v_mfma_f32_16x16x32_bf16 v[100:103], v[154:157], v[20:23], v[100:103]
	v_mfma_f32_16x16x32_bf16 v[84:87], v[154:157], v[32:35], v[84:87]
	s_waitcnt lgkmcnt(2)
	v_mfma_f32_16x16x32_bf16 v[104:107], v[158:161], v[20:23], v[104:107]
	v_mfma_f32_16x16x32_bf16 v[88:91], v[158:161], v[32:35], v[88:91]
	s_waitcnt lgkmcnt(1)
	v_mfma_f32_16x16x32_bf16 v[108:111], v[162:165], v[20:23], v[108:111]
	v_mfma_f32_16x16x32_bf16 v[92:95], v[162:165], v[32:35], v[92:95]
	s_waitcnt lgkmcnt(0)
	v_mfma_f32_16x16x32_bf16 v[112:115], v[166:169], v[20:23], v[112:115]
	v_mfma_f32_16x16x32_bf16 v[96:99], v[166:169], v[32:35], v[96:99]
	ds_read_b128 v[154:157], v0 offset:24704
	ds_read_b128 v[158:161], v0 offset:28288
	ds_read_b128 v[162:165], v0 offset:31872
	ds_read_b128 v[166:169], v0 offset:35456
	s_waitcnt lgkmcnt(3)
	v_mfma_f32_16x16x32_bf16 v[206:209], v[154:157], v[24:27], v[100:103]
	v_mfma_f32_16x16x32_bf16 v[212:215], v[154:157], v[36:39], v[84:87]
	s_waitcnt lgkmcnt(2)
	v_mfma_f32_16x16x32_bf16 v[154:157], v[158:161], v[24:27], v[104:107]
	v_mfma_f32_16x16x32_bf16 v[216:219], v[158:161], v[36:39], v[88:91]
	s_waitcnt lgkmcnt(1)
	v_mfma_f32_16x16x32_bf16 v[220:223], v[162:165], v[24:27], v[108:111]
	v_mfma_f32_16x16x32_bf16 v[224:227], v[162:165], v[36:39], v[92:95]
	s_waitcnt lgkmcnt(0)
	v_mfma_f32_16x16x32_bf16 v[228:231], v[166:169], v[24:27], v[112:115]
	v_mfma_f32_16x16x32_bf16 v[232:235], v[166:169], v[36:39], v[96:99]
	s_nop 1
	ds_read_b64_tr_b16 v[114:115], v176 offset:41472
	ds_read_b64_tr_b16 v[112:113], v176 offset:38912
	ds_read_b64_tr_b16 v[108:109], v176 offset:38944
	ds_read_b64_tr_b16 v[110:111], v176 offset:41504
	ds_read_b64_tr_b16 v[104:105], v176 offset:38976
	ds_read_b64_tr_b16 v[106:107], v176 offset:41536
	ds_read_b64_tr_b16 v[96:97], v176 offset:39008
	ds_read_b64_tr_b16 v[98:99], v176 offset:41568
	ds_read_b64_tr_b16 v[84:85], v176 offset:44032
	ds_read_b64_tr_b16 v[86:87], v176 offset:46592
	ds_read_b64_tr_b16 v[88:89], v176 offset:44064
	ds_read_b64_tr_b16 v[90:91], v176 offset:46624
	ds_read_b64_tr_b16 v[92:93], v176 offset:44096
	ds_read_b64_tr_b16 v[94:95], v176 offset:46656
	ds_read_b64_tr_b16 v[100:101], v176 offset:44128
	ds_read_b64_tr_b16 v[102:103], v176 offset:46688
	v_exp_f32_e32 v205, v206
	v_exp_f32_e32 v206, v207
	v_exp_f32_e32 v207, v208
	v_exp_f32_e32 v208, v209
	v_exp_f32_e32 v209, v154
	v_exp_f32_e32 v210, v155
	v_exp_f32_e32 v147, v156
	v_exp_f32_e32 v155, v157
	v_exp_f32_e32 v157, v220
	v_exp_f32_e32 v159, v221
	v_exp_f32_e32 v161, v222
	v_exp_f32_e32 v163, v223
	v_exp_f32_e32 v165, v228
	v_exp_f32_e32 v167, v229
	v_exp_f32_e32 v169, v230
	v_exp_f32_e32 v171, v231
	v_exp_f32_e32 v211, v212
	v_exp_f32_e32 v212, v213
	v_exp_f32_e32 v213, v214
	v_exp_f32_e32 v214, v215
	v_exp_f32_e32 v215, v216
	v_exp_f32_e32 v216, v217
	v_exp_f32_e32 v146, v218
	v_exp_f32_e32 v154, v219
	v_exp_f32_e32 v156, v224
	v_exp_f32_e32 v158, v225
	v_exp_f32_e32 v160, v226
	v_exp_f32_e32 v162, v227
	v_exp_f32_e32 v164, v232
	v_exp_f32_e32 v166, v233
	v_exp_f32_e32 v168, v234
	v_exp_f32_e32 v170, v235
	v_cvt_pk_bf16_f32 v218, v205, v206
	v_cvt_pk_bf16_f32 v219, v207, v208
	v_cvt_pk_bf16_f32 v220, v209, v210
	v_cvt_pk_bf16_f32 v221, v147, v155
	v_cvt_pk_bf16_f32 v222, v211, v212
	v_cvt_pk_bf16_f32 v223, v213, v214
	v_cvt_pk_bf16_f32 v224, v215, v216
	v_cvt_pk_bf16_f32 v225, v146, v154
	s_waitcnt lgkmcnt(14)
	v_mfma_f32_16x16x32_bf16 v[76:79], v[112:115], v[218:221], v[76:79]
	s_andn2_b64 vcc, exec, s[26:27]
	v_mfma_f32_16x16x32_bf16 v[112:115], v[112:115], v[222:225], v[80:83]
	s_waitcnt lgkmcnt(12)
	v_mfma_f32_16x16x32_bf16 v[226:229], v[108:111], v[218:221], v[72:75]
	v_mfma_f32_16x16x32_bf16 v[68:71], v[108:111], v[222:225], v[68:71]
	s_waitcnt lgkmcnt(10)
	v_mfma_f32_16x16x32_bf16 v[64:67], v[104:107], v[218:221], v[64:67]
	v_mfma_f32_16x16x32_bf16 v[104:107], v[104:107], v[222:225], v[10:13]
	s_waitcnt lgkmcnt(8)
	v_mfma_f32_16x16x32_bf16 v[108:111], v[96:99], v[218:221], v[6:9]
	v_cvt_pk_bf16_f32 v218, v156, v158
	v_cvt_pk_bf16_f32 v219, v160, v162
	v_cvt_pk_bf16_f32 v220, v164, v166
	v_mfma_f32_16x16x32_bf16 v[2:5], v[96:99], v[222:225], v[2:5]
	v_cvt_pk_bf16_f32 v96, v157, v159
	v_cvt_pk_bf16_f32 v97, v161, v163
	v_cvt_pk_bf16_f32 v98, v165, v167
	v_cvt_pk_bf16_f32 v99, v169, v171
	v_cvt_pk_bf16_f32 v221, v168, v170
	s_waitcnt lgkmcnt(6)
	v_mfma_f32_16x16x32_bf16 v[80:83], v[84:87], v[96:99], v[76:79]
	v_mfma_f32_16x16x32_bf16 v[72:75], v[84:87], v[218:221], v[112:115]
	s_waitcnt lgkmcnt(4)
	v_mfma_f32_16x16x32_bf16 v[76:79], v[88:91], v[96:99], v[226:229]
	v_mfma_f32_16x16x32_bf16 v[12:15], v[88:91], v[218:221], v[68:71]
	s_waitcnt lgkmcnt(2)
	v_mfma_f32_16x16x32_bf16 v[68:71], v[92:95], v[96:99], v[64:67]
	v_mfma_f32_16x16x32_bf16 v[8:11], v[92:95], v[218:221], v[104:107]
	s_waitcnt lgkmcnt(0)
	v_mfma_f32_16x16x32_bf16 v[64:67], v[100:103], v[96:99], v[108:111]
	v_mfma_f32_16x16x32_bf16 v[4:7], v[100:103], v[218:221], v[2:5]
	s_cbranch_vccnz .LBB0_1135
	s_and_saveexec_b64 s[26:27], s[40:41]
	s_nop 0
	v_add_u32_e32 v2, v174, v150
	ds_write_b128 v2, v[40:43]
	s_or_b64 exec, exec, s[26:27]
	s_and_saveexec_b64 s[26:27], s[48:49]
	s_cbranch_execz .LBB0_1134
	v_add_u32_e32 v2, v175, v152
	ds_write_b128 v2, v[44:47]
	s_branch .LBB0_1134
